# v26
# speedup vs baseline: 1.0179x; 1.0146x over previous
.LBB0_218:
	s_or_b64 exec, exec, s[12:13]
	v_add_u32_e32 v2, v147, v2
	v_and_b32_e32 v2, 0xfffffc00, v2
	v_sub_u32_e32 v2, v147, v2
	v_lshrrev_b32_e32 v6, 4, v2
	v_bitop3_b32 v2, v6, v2, 32 bitop3:0x6c
	v_ashrrev_i32_e32 v7, 31, v2
	v_add_u32_e32 v3, v146, v3
	v_lshrrev_b32_e32 v7, 26, v7
	s_ashr_i32 s13, s75, 31
	v_ashrrev_i32_e32 v3, 6, v3
	v_add_u32_e32 v7, v2, v7
	s_mul_i32 s18, s13, s15
	v_lshlrev_b32_e32 v6, 3, v3
	v_ashrrev_i32_e32 v8, 6, v7
	v_and_b32_e32 v7, 0xc0, v7
	s_add_i32 s11, s17, s18
	v_and_b32_e32 v6, -16, v6
	v_sub_u32_e32 v2, v2, v7
	s_lshr_b32 s12, s15, 6
	s_lshl_b64 s[10:11], s[10:11], 1
	v_add_u32_e32 v6, v8, v6
	v_lshlrev_b32_e32 v3, 5, v3
	v_ashrrev_i16_sdwa v2, v205, sext(v2) dst_sel:DWORD dst_unused:UNUSED_PAD src0_sel:DWORD src1_sel:BYTE_0
	s_add_u32 s10, s6, s10
	v_and_b32_e32 v3, 32, v3
	v_bfe_i32 v2, v2, 0, 16
	v_mul_lo_u32 v6, v6, s15
	s_addc_u32 s11, s7, s11
	v_add3_u32 v180, v6, v3, v2
	s_add_i32 s17, 0, 0x18000
	v_lshlrev_b64 v[2:3], 1, v[180:181]
	v_add_u32_e32 v154, s17, v147
	v_lshl_add_u64 v[130:131], s[10:11], 0, v[2:3]
	v_readfirstlane_b32 s9, v154
	v_lshl_add_u64 v[6:7], v[130:131], 0, s[28:29]
	s_mov_b32 m0, s9
	s_waitcnt vmcnt(4)
	s_barrier
	global_load_lds_dwordx4 v[6:7], off
	v_ashrrev_i32_e32 v6, 31, v1
	v_lshrrev_b32_e32 v6, 22, v6
	v_add_u32_e32 v6, v1, v6
	v_ashrrev_i32_e32 v6, 10, v6
	v_mul_i32_i24_e32 v7, 0x400, v6
	v_sub_u32_e32 v7, v1, v7
	v_lshrrev_b32_e32 v8, 4, v7
	v_bitop3_b32 v7, v8, v7, 32 bitop3:0x6c
	v_ashrrev_i32_e32 v9, 31, v7
	v_lshrrev_b32_e32 v9, 26, v9
	v_lshlrev_b32_e32 v8, 3, v6
	v_add_u32_e32 v9, v7, v9
	v_and_b32_e32 v8, -16, v8
	v_ashrrev_i32_e32 v11, 6, v9
	v_add_u32_e32 v8, v11, v8
	v_and_b32_e32 v9, 0xc0, v9
	v_add_u32_e32 v11, s17, v1
	v_sub_u32_e32 v7, v7, v9
	v_readfirstlane_b32 s9, v11
	s_ashr_i32 s61, s60, 31
	v_lshlrev_b32_e32 v6, 5, v6
	v_ashrrev_i16_sdwa v7, v205, sext(v7) dst_sel:DWORD dst_unused:UNUSED_PAD src0_sel:DWORD src1_sel:BYTE_0
	s_mov_b32 m0, s9
	s_mul_i32 s9, s61, s15
	v_and_b32_e32 v6, 32, v6
	v_bfe_i32 v7, v7, 0, 16
	v_mul_lo_u32 v8, v8, s15
	s_add_i32 s9, s16, s9
	v_add3_u32 v128, v8, v6, v7
	v_mov_b32_e32 v129, v181
	s_lshl_b64 s[8:9], s[8:9], 1
	v_lshlrev_b64 v[6:7], 1, v[128:129]
	s_add_u32 s8, s4, s8
	v_lshl_add_u64 v[132:133], s[10:11], 0, v[6:7]
	s_addc_u32 s9, s5, s9
	v_add_u32_e32 v156, 0x8000, v148
	v_lshl_add_u64 v[8:9], v[132:133], 0, s[28:29]
	v_lshl_add_u64 v[134:135], s[8:9], 0, v[2:3]
	v_readfirstlane_b32 s10, v156
	v_add_u32_e32 v157, 0xa000, v148
	global_load_lds_dwordx4 v[8:9], off
	v_lshl_add_u64 v[8:9], v[134:135], 0, s[28:29]
	s_mov_b32 m0, s10
	v_lshl_add_u64 v[136:137], s[8:9], 0, v[6:7]
	v_readfirstlane_b32 s8, v157
	global_load_lds_dwordx4 v[8:9], off
	s_mov_b32 m0, s8
	s_or_b32 s8, s75, 0x80
	s_mul_hi_u32 s9, s8, s15
	s_add_i32 s9, s9, s18
	s_mul_i32 s8, s8, s15
	s_lshl_b64 s[8:9], s[8:9], 1
	s_add_u32 s8, s6, s8
	v_lshl_add_u64 v[8:9], v[136:137], 0, s[28:29]
	s_addc_u32 s9, s7, s9
	v_add_u32_e32 v158, s72, v147
	global_load_lds_dwordx4 v[8:9], off
	v_lshl_add_u64 v[8:9], s[8:9], 0, v[2:3]
	v_readfirstlane_b32 s10, v158
	v_lshl_add_u64 v[8:9], v[8:9], 0, s[28:29]
	s_mov_b32 m0, s10
	v_add_u32_e32 v1, s72, v1
	global_load_lds_dwordx4 v[8:9], off
	v_lshl_add_u64 v[8:9], s[8:9], 0, v[6:7]
	v_readfirstlane_b32 s8, v1
	v_lshl_add_u64 v[8:9], v[8:9], 0, s[28:29]
	s_mov_b32 m0, s8
	v_and_b32_e32 v5, 15, v0
	global_load_lds_dwordx4 v[8:9], off
	v_and_b32_e32 v10, 48, v0
	s_add_i32 s10, s12, -2
	v_lshlrev_b32_e32 v1, 6, v5
	v_lshlrev_b32_e32 v5, 2, v0
	s_add_i32 s9, 0, 0x10000
	s_add_i32 s8, 0, 0x14000
	v_lshlrev_b32_e32 v0, 6, v0
	s_movk_i32 s11, 0x3c0
	v_and_or_b32 v0, v0, s11, v10
	s_add_u32 s11, s75, 0x80
	v_and_b32_e32 v5, 32, v5
	s_addc_u32 s13, s13, 0
	v_bitop3_b32 v1, v1, v5, v10 bitop3:0x36
	s_mul_i32 s13, s13, s15
	s_mul_hi_u32 s16, s11, s15
	v_add_u32_e32 v11, s17, v1
	s_add_i32 s17, s16, s13
	s_mul_i32 s16, s11, s15
	s_lshl_b64 s[16:17], s[16:17], 1
	s_add_u32 s6, s6, s16
	s_addc_u32 s7, s7, s17
	v_lshl_add_u64 v[138:139], s[6:7], 0, v[6:7]
	v_lshl_add_u64 v[140:141], s[6:7], 0, v[2:3]
	s_add_u32 s6, s60, 0x80
	s_addc_u32 s7, s61, 0
	s_mul_i32 s7, s7, s15
	s_mul_hi_u32 s11, s6, s15
	s_add_i32 s7, s11, s7
	s_mul_i32 s6, s6, s15
	s_lshl_b64 s[6:7], s[6:7], 1
	s_waitcnt vmcnt(6)
	v_lshlrev_b32_e32 v13, 6, v146
	v_lshlrev_b32_e32 v4, 13, v4
	s_add_u32 s6, s4, s6
	v_add_u32_e32 v8, s9, v1
	v_add_u32_e32 v9, s8, v1
	v_add_u32_e32 v12, s72, v1
	v_and_b32_e32 v13, 0x3000, v13
	v_add_u32_e32 v1, 0, v1
	v_xad_u32 v5, v0, v5, 0
	v_or_b32_e32 v10, 0x800, v4
	v_or_b32_e32 v14, 0x1000, v4
	v_or_b32_e32 v15, 0x1800, v4
	s_addc_u32 s7, s5, s7
	v_mov_b32_e32 v0, 0
	v_lshl_add_u64 v[142:143], s[6:7], 0, v[6:7]
	v_lshl_add_u64 v[144:145], s[6:7], 0, v[2:3]
	s_mov_b32 s11, 0
	s_mov_b64 s[6:7], 0
	s_waitcnt vmcnt(0)
	v_add_u32_e32 v160, v8, v13
	v_add_u32_e32 v152, v1, v4
	v_add_u32_e32 v151, v5, v10
	v_add_u32_e32 v150, v5, v14
	v_add_u32_e32 v149, v5, v15
	v_add_u32_e32 v159, v9, v13
	v_add_u32_e32 v155, v11, v13
	v_add_u32_e32 v153, v12, v13
	v_mov_b32_e32 v1, v0
	v_mov_b32_e32 v2, v0
	v_mov_b32_e32 v3, v0
	v_mov_b32_e32 v4, v0
	v_mov_b32_e32 v5, v0
	v_mov_b32_e32 v6, v0
	v_mov_b32_e32 v7, v0
	v_mov_b32_e32 v8, v0
	v_mov_b32_e32 v9, v0
	v_mov_b32_e32 v10, v0
	v_mov_b32_e32 v11, v0
	v_mov_b32_e32 v12, v0
	v_mov_b32_e32 v13, v0
	v_mov_b32_e32 v14, v0
	v_mov_b32_e32 v15, v0
	v_mov_b32_e32 v16, v0
	v_mov_b32_e32 v17, v0
	v_mov_b32_e32 v18, v0
	v_mov_b32_e32 v19, v0
	v_mov_b32_e32 v20, v0
	v_mov_b32_e32 v21, v0
	v_mov_b32_e32 v22, v0
	v_mov_b32_e32 v23, v0
	v_mov_b32_e32 v24, v0
	v_mov_b32_e32 v25, v0
	v_mov_b32_e32 v26, v0
	v_mov_b32_e32 v27, v0
	v_mov_b32_e32 v28, v0
	v_mov_b32_e32 v29, v0
	v_mov_b32_e32 v30, v0
	v_mov_b32_e32 v31, v0
	v_mov_b32_e32 v32, v0
	v_mov_b32_e32 v33, v0
	v_mov_b32_e32 v34, v0
	v_mov_b32_e32 v35, v0
	v_mov_b32_e32 v36, v0
	v_mov_b32_e32 v37, v0
	v_mov_b32_e32 v38, v0
	v_mov_b32_e32 v39, v0
	v_mov_b32_e32 v40, v0
	v_mov_b32_e32 v41, v0
	v_mov_b32_e32 v42, v0
	v_mov_b32_e32 v43, v0
	v_mov_b32_e32 v44, v0
	v_mov_b32_e32 v45, v0
	v_mov_b32_e32 v46, v0
	v_mov_b32_e32 v47, v0
	v_mov_b32_e32 v48, v0
	v_mov_b32_e32 v49, v0
	v_mov_b32_e32 v50, v0
	v_mov_b32_e32 v51, v0
	v_mov_b32_e32 v52, v0
	v_mov_b32_e32 v53, v0
	v_mov_b32_e32 v54, v0
	v_mov_b32_e32 v55, v0
	v_mov_b32_e32 v56, v0
	v_mov_b32_e32 v57, v0
	v_mov_b32_e32 v58, v0
	v_mov_b32_e32 v59, v0
	v_mov_b32_e32 v60, v0
	v_mov_b32_e32 v61, v0
	v_mov_b32_e32 v62, v0
	v_mov_b32_e32 v63, v0
	v_mov_b32_e32 v64, v0
	v_mov_b32_e32 v65, v0
	v_mov_b32_e32 v66, v0
	v_mov_b32_e32 v67, v0
	v_mov_b32_e32 v68, v0
	v_mov_b32_e32 v69, v0
	v_mov_b32_e32 v70, v0
	v_mov_b32_e32 v71, v0
	v_mov_b32_e32 v72, v0
	v_mov_b32_e32 v73, v0
	v_mov_b32_e32 v74, v0
	v_mov_b32_e32 v75, v0
	v_mov_b32_e32 v76, v0
	v_mov_b32_e32 v77, v0
	v_mov_b32_e32 v78, v0
	v_mov_b32_e32 v79, v0
	v_mov_b32_e32 v80, v0
	v_mov_b32_e32 v81, v0
	v_mov_b32_e32 v82, v0
	v_mov_b32_e32 v83, v0
	v_mov_b32_e32 v84, v0
	v_mov_b32_e32 v85, v0
	v_mov_b32_e32 v86, v0
	v_mov_b32_e32 v87, v0
	v_mov_b32_e32 v88, v0
	v_mov_b32_e32 v89, v0
	v_mov_b32_e32 v90, v0
	v_mov_b32_e32 v91, v0
	v_mov_b32_e32 v92, v0
	v_mov_b32_e32 v93, v0
	v_mov_b32_e32 v94, v0
	v_mov_b32_e32 v95, v0
	v_mov_b32_e32 v96, v0
	v_mov_b32_e32 v97, v0
	v_mov_b32_e32 v98, v0
	v_mov_b32_e32 v99, v0
	v_mov_b32_e32 v100, v0
	v_mov_b32_e32 v101, v0
	v_mov_b32_e32 v102, v0
	v_mov_b32_e32 v103, v0
	v_mov_b32_e32 v104, v0
	v_mov_b32_e32 v105, v0
	v_mov_b32_e32 v106, v0
	v_mov_b32_e32 v107, v0
	v_mov_b32_e32 v108, v0
	v_mov_b32_e32 v109, v0
	v_mov_b32_e32 v110, v0
	v_mov_b32_e32 v111, v0
	v_mov_b32_e32 v112, v0
	v_mov_b32_e32 v113, v0
	v_mov_b32_e32 v114, v0
	v_mov_b32_e32 v115, v0
	v_mov_b32_e32 v116, v0
	v_mov_b32_e32 v117, v0
	v_mov_b32_e32 v118, v0
	v_mov_b32_e32 v119, v0
	v_mov_b32_e32 v120, v0
	v_mov_b32_e32 v121, v0
	v_mov_b32_e32 v122, v0
	v_mov_b32_e32 v123, v0
	v_mov_b32_e32 v124, v0
	v_mov_b32_e32 v125, v0
	v_mov_b32_e32 v126, v0
	v_mov_b32_e32 v127, v0
	v_readfirstlane_b32 s100, v148
	v_readfirstlane_b32 s101, v147
	s_barrier
.LBB0_219:
	ds_read_b128 v[164:167], v160
	ds_read_b128 v[168:171], v160 offset:1024
	ds_read_b128 v[172:175], v160 offset:2048
	ds_read_b128 v[176:179], v160 offset:3072
	v_lshl_add_u64 v[240:241], v[144:145], 0, s[6:7]
	v_lshl_add_u64 v[162:163], v[240:241], 0, s[28:29]
	s_add_i32 m0, s100, 0xc000
	ds_read_b128 v[184:187], v152
	ds_read_b128 v[190:193], v152 offset:1024
	ds_read_b128 v[194:197], v151
	ds_read_b128 v[198:201], v151 offset:1024
	ds_read_b128 v[206:209], v150
	ds_read_b128 v[212:215], v150 offset:1024
	ds_read_b128 v[216:219], v149
	ds_read_b128 v[220:223], v149 offset:1024
	global_load_lds_dwordx4 v[162:163], off
	v_lshl_add_u64 v[242:243], v[142:143], 0, s[6:7]
	v_lshl_add_u64 v[224:225], v[242:243], 0, s[28:29]
	s_add_i32 m0, s100, 0xe000
	s_nop 0
	global_load_lds_dwordx4 v[224:225], off
	s_waitcnt lgkmcnt(8)
	s_barrier
	s_waitcnt lgkmcnt(0)
	s_setprio 1
	s_waitcnt lgkmcnt(0)
	v_mfma_f32_16x16x32_bf16 v[124:127], v[184:187], v[164:167], v[124:127]
	v_mfma_f32_16x16x32_bf16 v[120:123], v[184:187], v[172:175], v[120:123]
	v_mfma_f32_16x16x32_bf16 v[116:119], v[194:197], v[164:167], v[116:119]
	v_mfma_f32_16x16x32_bf16 v[112:115], v[194:197], v[172:175], v[112:115]
	v_mfma_f32_16x16x32_bf16 v[108:111], v[206:209], v[164:167], v[108:111]
	v_mfma_f32_16x16x32_bf16 v[104:107], v[206:209], v[172:175], v[104:107]
	v_mfma_f32_16x16x32_bf16 v[100:103], v[216:219], v[164:167], v[100:103]
	v_mfma_f32_16x16x32_bf16 v[96:99], v[216:219], v[172:175], v[96:99]
	v_mfma_f32_16x16x32_bf16 v[124:127], v[190:193], v[168:171], v[124:127]
	v_mfma_f32_16x16x32_bf16 v[120:123], v[190:193], v[176:179], v[120:123]
	v_mfma_f32_16x16x32_bf16 v[116:119], v[198:201], v[168:171], v[116:119]
	v_mfma_f32_16x16x32_bf16 v[112:115], v[198:201], v[176:179], v[112:115]
	v_mfma_f32_16x16x32_bf16 v[108:111], v[212:215], v[168:171], v[108:111]
	v_mfma_f32_16x16x32_bf16 v[104:107], v[212:215], v[176:179], v[104:107]
	v_mfma_f32_16x16x32_bf16 v[100:103], v[220:223], v[168:171], v[100:103]
	v_mfma_f32_16x16x32_bf16 v[96:99], v[220:223], v[176:179], v[96:99]
	s_setprio 0
	s_barrier
	v_lshl_add_u64 v[244:245], v[130:131], 0, s[6:7]
	v_lshl_add_u64 v[246:247], v[244:245], 0, s[64:65]
	s_add_i32 m0, s101, 0x10000
	ds_read_b128 v[224:227], v159
	ds_read_b128 v[228:231], v159 offset:1024
	ds_read_b128 v[232:235], v159 offset:2048
	ds_read_b128 v[236:239], v159 offset:3072
	global_load_lds_dwordx4 v[246:247], off
	v_lshl_add_u64 v[246:247], v[132:133], 0, s[6:7]
	v_lshl_add_u64 v[248:249], v[246:247], 0, s[64:65]
	s_add_i32 m0, m0, 0x2000
	s_add_i32 s11, s11, 2
	global_load_lds_dwordx4 v[248:249], off
	s_barrier
	s_waitcnt lgkmcnt(0)
	s_setprio 1
	s_waitcnt lgkmcnt(0)
	v_mfma_f32_16x16x32_bf16 v[92:95], v[184:187], v[224:227], v[92:95]
	v_mfma_f32_16x16x32_bf16 v[88:91], v[184:187], v[232:235], v[88:91]
	v_mfma_f32_16x16x32_bf16 v[84:87], v[194:197], v[224:227], v[84:87]
	v_mfma_f32_16x16x32_bf16 v[80:83], v[194:197], v[232:235], v[80:83]
	v_mfma_f32_16x16x32_bf16 v[76:79], v[206:209], v[224:227], v[76:79]
	v_mfma_f32_16x16x32_bf16 v[72:75], v[206:209], v[232:235], v[72:75]
	v_mfma_f32_16x16x32_bf16 v[68:71], v[216:219], v[224:227], v[68:71]
	v_mfma_f32_16x16x32_bf16 v[64:67], v[216:219], v[232:235], v[64:67]
	v_mfma_f32_16x16x32_bf16 v[92:95], v[190:193], v[228:231], v[92:95]
	v_mfma_f32_16x16x32_bf16 v[88:91], v[190:193], v[236:239], v[88:91]
	v_mfma_f32_16x16x32_bf16 v[84:87], v[198:201], v[228:231], v[84:87]
	v_mfma_f32_16x16x32_bf16 v[80:83], v[198:201], v[236:239], v[80:83]
	v_mfma_f32_16x16x32_bf16 v[76:79], v[212:215], v[228:231], v[76:79]
	v_mfma_f32_16x16x32_bf16 v[72:75], v[212:215], v[236:239], v[72:75]
	v_mfma_f32_16x16x32_bf16 v[68:71], v[220:223], v[228:231], v[68:71]
	v_mfma_f32_16x16x32_bf16 v[64:67], v[220:223], v[236:239], v[64:67]
	s_setprio 0
	v_lshl_add_u64 v[248:249], v[134:135], 0, s[6:7]
	v_lshl_add_u64 v[250:251], v[248:249], 0, s[64:65]
	s_mov_b32 m0, s100
	s_barrier
	ds_read_b128 v[184:187], v152 offset:16384
	ds_read_b128 v[190:193], v152 offset:17408
	ds_read_b128 v[194:197], v151 offset:16384
	ds_read_b128 v[198:201], v151 offset:17408
	ds_read_b128 v[206:209], v150 offset:16384
	ds_read_b128 v[212:215], v150 offset:17408
	ds_read_b128 v[216:219], v149 offset:16384
	ds_read_b128 v[220:223], v149 offset:17408
	global_load_lds_dwordx4 v[250:251], off
	v_lshl_add_u64 v[250:251], v[136:137], 0, s[6:7]
	v_lshl_add_u64 v[252:253], v[250:251], 0, s[64:65]
	s_add_i32 m0, s100, 0x2000
	s_nop 0
	global_load_lds_dwordx4 v[252:253], off
	s_barrier
	s_waitcnt lgkmcnt(0)
	s_setprio 1
	s_waitcnt lgkmcnt(0)
	v_mfma_f32_16x16x32_bf16 v[60:63], v[184:187], v[164:167], v[60:63]
	v_mfma_f32_16x16x32_bf16 v[56:59], v[184:187], v[172:175], v[56:59]
	v_mfma_f32_16x16x32_bf16 v[52:55], v[194:197], v[164:167], v[52:55]
	v_mfma_f32_16x16x32_bf16 v[48:51], v[194:197], v[172:175], v[48:51]
	v_mfma_f32_16x16x32_bf16 v[44:47], v[206:209], v[164:167], v[44:47]
	v_mfma_f32_16x16x32_bf16 v[40:43], v[206:209], v[172:175], v[40:43]
	v_mfma_f32_16x16x32_bf16 v[36:39], v[216:219], v[164:167], v[36:39]
	v_mfma_f32_16x16x32_bf16 v[32:35], v[216:219], v[172:175], v[32:35]
	v_mfma_f32_16x16x32_bf16 v[60:63], v[190:193], v[168:171], v[60:63]
	v_mfma_f32_16x16x32_bf16 v[56:59], v[190:193], v[176:179], v[56:59]
	v_mfma_f32_16x16x32_bf16 v[52:55], v[198:201], v[168:171], v[52:55]
	v_mfma_f32_16x16x32_bf16 v[48:51], v[198:201], v[176:179], v[48:51]
	v_mfma_f32_16x16x32_bf16 v[44:47], v[212:215], v[168:171], v[44:47]
	v_mfma_f32_16x16x32_bf16 v[40:43], v[212:215], v[176:179], v[40:43]
	v_mfma_f32_16x16x32_bf16 v[36:39], v[220:223], v[168:171], v[36:39]
	v_mfma_f32_16x16x32_bf16 v[32:35], v[220:223], v[176:179], v[32:35]
	s_setprio 0
	s_barrier
	v_lshl_add_u64 v[252:253], v[140:141], 0, s[6:7]
	v_lshl_add_u64 v[164:165], v[252:253], 0, s[64:65]
	s_add_i32 m0, s101, 0x14000
	v_lshl_add_u64 v[188:189], v[138:139], 0, s[6:7]
	global_load_lds_dwordx4 v[164:165], off
	v_lshl_add_u64 v[164:165], v[188:189], 0, s[64:65]
	s_add_i32 m0, m0, 0x2000
	s_nop 0
	global_load_lds_dwordx4 v[164:165], off
	s_waitcnt vmcnt(6)
	s_barrier
	s_setprio 1
	v_mfma_f32_16x16x32_bf16 v[28:31], v[184:187], v[224:227], v[28:31]
	v_mfma_f32_16x16x32_bf16 v[24:27], v[184:187], v[232:235], v[24:27]
	v_mfma_f32_16x16x32_bf16 v[20:23], v[194:197], v[224:227], v[20:23]
	v_mfma_f32_16x16x32_bf16 v[16:19], v[194:197], v[232:235], v[16:19]
	v_mfma_f32_16x16x32_bf16 v[12:15], v[206:209], v[224:227], v[12:15]
	v_mfma_f32_16x16x32_bf16 v[8:11], v[206:209], v[232:235], v[8:11]
	v_mfma_f32_16x16x32_bf16 v[4:7], v[216:219], v[224:227], v[4:7]
	v_mfma_f32_16x16x32_bf16 v[0:3], v[216:219], v[232:235], v[0:3]
	v_mfma_f32_16x16x32_bf16 v[28:31], v[190:193], v[228:231], v[28:31]
	v_mfma_f32_16x16x32_bf16 v[24:27], v[190:193], v[236:239], v[24:27]
	v_mfma_f32_16x16x32_bf16 v[20:23], v[198:201], v[228:231], v[20:23]
	v_mfma_f32_16x16x32_bf16 v[16:19], v[198:201], v[236:239], v[16:19]
	v_mfma_f32_16x16x32_bf16 v[12:15], v[212:215], v[228:231], v[12:15]
	v_mfma_f32_16x16x32_bf16 v[8:11], v[212:215], v[236:239], v[8:11]
	v_mfma_f32_16x16x32_bf16 v[4:7], v[220:223], v[228:231], v[4:7]
	v_mfma_f32_16x16x32_bf16 v[0:3], v[220:223], v[236:239], v[0:3]
	s_setprio 0
	s_barrier
	ds_read_b128 v[164:167], v155
	ds_read_b128 v[168:171], v155 offset:1024
	ds_read_b128 v[172:175], v155 offset:2048
	ds_read_b128 v[176:179], v155 offset:3072
	v_lshl_add_u64 v[224:225], v[240:241], 0, s[64:65]
	s_add_i32 m0, s100, 0x4000
	ds_read_b128 v[184:187], v152 offset:32768
	ds_read_b128 v[190:193], v152 offset:33792
	ds_read_b128 v[194:197], v151 offset:32768
	ds_read_b128 v[198:201], v151 offset:33792
	ds_read_b128 v[206:209], v150 offset:32768
	ds_read_b128 v[212:215], v150 offset:33792
	ds_read_b128 v[216:219], v149 offset:32768
	ds_read_b128 v[220:223], v149 offset:33792
	global_load_lds_dwordx4 v[224:225], off
	v_lshl_add_u64 v[224:225], v[242:243], 0, s[64:65]
	s_add_i32 m0, s100, 0x6000
	s_nop 0
	global_load_lds_dwordx4 v[224:225], off
	s_waitcnt lgkmcnt(8)
	s_barrier
	s_waitcnt lgkmcnt(0)
	s_setprio 1
	s_waitcnt lgkmcnt(0)
	v_mfma_f32_16x16x32_bf16 v[124:127], v[184:187], v[164:167], v[124:127]
	v_mfma_f32_16x16x32_bf16 v[120:123], v[184:187], v[172:175], v[120:123]
	v_mfma_f32_16x16x32_bf16 v[116:119], v[194:197], v[164:167], v[116:119]
	v_mfma_f32_16x16x32_bf16 v[112:115], v[194:197], v[172:175], v[112:115]
	v_mfma_f32_16x16x32_bf16 v[108:111], v[206:209], v[164:167], v[108:111]
	v_mfma_f32_16x16x32_bf16 v[104:107], v[206:209], v[172:175], v[104:107]
	v_mfma_f32_16x16x32_bf16 v[100:103], v[216:219], v[164:167], v[100:103]
	v_mfma_f32_16x16x32_bf16 v[96:99], v[216:219], v[172:175], v[96:99]
	v_mfma_f32_16x16x32_bf16 v[124:127], v[190:193], v[168:171], v[124:127]
	v_mfma_f32_16x16x32_bf16 v[120:123], v[190:193], v[176:179], v[120:123]
	v_mfma_f32_16x16x32_bf16 v[116:119], v[198:201], v[168:171], v[116:119]
	v_mfma_f32_16x16x32_bf16 v[112:115], v[198:201], v[176:179], v[112:115]
	v_mfma_f32_16x16x32_bf16 v[108:111], v[212:215], v[168:171], v[108:111]
	v_mfma_f32_16x16x32_bf16 v[104:107], v[212:215], v[176:179], v[104:107]
	v_mfma_f32_16x16x32_bf16 v[100:103], v[220:223], v[168:171], v[100:103]
	v_mfma_f32_16x16x32_bf16 v[96:99], v[220:223], v[176:179], v[96:99]
	s_setprio 0
	s_barrier
	v_lshl_add_u64 v[240:241], v[244:245], 0, s[92:93]
	s_add_i32 m0, s101, 0x18000
	ds_read_b128 v[224:227], v153
	ds_read_b128 v[228:231], v153 offset:1024
	ds_read_b128 v[232:235], v153 offset:2048
	ds_read_b128 v[236:239], v153 offset:3072
	global_load_lds_dwordx4 v[240:241], off
	v_lshl_add_u64 v[240:241], v[246:247], 0, s[92:93]
	s_add_i32 m0, m0, 0x2000
	s_nop 0
	global_load_lds_dwordx4 v[240:241], off
	s_barrier
	s_waitcnt lgkmcnt(0)
	s_setprio 1
	s_waitcnt lgkmcnt(0)
	v_mfma_f32_16x16x32_bf16 v[92:95], v[184:187], v[224:227], v[92:95]
	v_mfma_f32_16x16x32_bf16 v[88:91], v[184:187], v[232:235], v[88:91]
	v_mfma_f32_16x16x32_bf16 v[84:87], v[194:197], v[224:227], v[84:87]
	v_mfma_f32_16x16x32_bf16 v[80:83], v[194:197], v[232:235], v[80:83]
	v_mfma_f32_16x16x32_bf16 v[76:79], v[206:209], v[224:227], v[76:79]
	v_mfma_f32_16x16x32_bf16 v[72:75], v[206:209], v[232:235], v[72:75]
	v_mfma_f32_16x16x32_bf16 v[68:71], v[216:219], v[224:227], v[68:71]
	v_mfma_f32_16x16x32_bf16 v[64:67], v[216:219], v[232:235], v[64:67]
	v_mfma_f32_16x16x32_bf16 v[92:95], v[190:193], v[228:231], v[92:95]
	v_mfma_f32_16x16x32_bf16 v[88:91], v[190:193], v[236:239], v[88:91]
	v_mfma_f32_16x16x32_bf16 v[84:87], v[198:201], v[228:231], v[84:87]
	v_mfma_f32_16x16x32_bf16 v[80:83], v[198:201], v[236:239], v[80:83]
	v_mfma_f32_16x16x32_bf16 v[76:79], v[212:215], v[228:231], v[76:79]
	v_mfma_f32_16x16x32_bf16 v[72:75], v[212:215], v[236:239], v[72:75]
	v_mfma_f32_16x16x32_bf16 v[68:71], v[220:223], v[228:231], v[68:71]
	v_mfma_f32_16x16x32_bf16 v[64:67], v[220:223], v[236:239], v[64:67]
	s_setprio 0
	v_lshl_add_u64 v[240:241], v[248:249], 0, s[92:93]
	s_add_i32 m0, s100, 0x8000
	s_barrier
	ds_read_b128 v[184:187], v152 offset:49152
	ds_read_b128 v[190:193], v152 offset:50176
	ds_read_b128 v[194:197], v151 offset:49152
	ds_read_b128 v[198:201], v151 offset:50176
	ds_read_b128 v[206:209], v150 offset:49152
	ds_read_b128 v[212:215], v150 offset:50176
	ds_read_b128 v[216:219], v149 offset:49152
	ds_read_b128 v[220:223], v149 offset:50176
	global_load_lds_dwordx4 v[240:241], off
	v_lshl_add_u64 v[240:241], v[250:251], 0, s[92:93]
	s_add_i32 m0, s100, 0xa000
	s_nop 0
	global_load_lds_dwordx4 v[240:241], off
	s_barrier
	s_waitcnt lgkmcnt(0)
	s_setprio 1
	s_waitcnt lgkmcnt(0)
	v_mfma_f32_16x16x32_bf16 v[60:63], v[184:187], v[164:167], v[60:63]
	v_mfma_f32_16x16x32_bf16 v[56:59], v[184:187], v[172:175], v[56:59]
	v_mfma_f32_16x16x32_bf16 v[52:55], v[194:197], v[164:167], v[52:55]
	v_mfma_f32_16x16x32_bf16 v[48:51], v[194:197], v[172:175], v[48:51]
	v_mfma_f32_16x16x32_bf16 v[44:47], v[206:209], v[164:167], v[44:47]
	v_mfma_f32_16x16x32_bf16 v[40:43], v[206:209], v[172:175], v[40:43]
	v_mfma_f32_16x16x32_bf16 v[36:39], v[216:219], v[164:167], v[36:39]
	v_mfma_f32_16x16x32_bf16 v[32:35], v[216:219], v[172:175], v[32:35]
	v_mfma_f32_16x16x32_bf16 v[60:63], v[190:193], v[168:171], v[60:63]
	v_mfma_f32_16x16x32_bf16 v[56:59], v[190:193], v[176:179], v[56:59]
	v_mfma_f32_16x16x32_bf16 v[52:55], v[198:201], v[168:171], v[52:55]
	v_mfma_f32_16x16x32_bf16 v[48:51], v[198:201], v[176:179], v[48:51]
	v_mfma_f32_16x16x32_bf16 v[44:47], v[212:215], v[168:171], v[44:47]
	v_mfma_f32_16x16x32_bf16 v[40:43], v[212:215], v[176:179], v[40:43]
	v_mfma_f32_16x16x32_bf16 v[36:39], v[220:223], v[168:171], v[36:39]
	v_mfma_f32_16x16x32_bf16 v[32:35], v[220:223], v[176:179], v[32:35]
	s_setprio 0
	s_barrier
	v_lshl_add_u64 v[164:165], v[252:253], 0, s[92:93]
	s_add_i32 m0, s101, 0x1c000
	s_nop 0
	global_load_lds_dwordx4 v[164:165], off
	v_lshl_add_u64 v[164:165], v[188:189], 0, s[92:93]
	s_add_i32 m0, m0, 0x2000
	s_nop 0
	global_load_lds_dwordx4 v[164:165], off
	s_waitcnt vmcnt(6)
	s_barrier
	s_setprio 1
	v_mfma_f32_16x16x32_bf16 v[28:31], v[184:187], v[224:227], v[28:31]
	v_mfma_f32_16x16x32_bf16 v[24:27], v[184:187], v[232:235], v[24:27]
	v_mfma_f32_16x16x32_bf16 v[20:23], v[194:197], v[224:227], v[20:23]
	v_mfma_f32_16x16x32_bf16 v[16:19], v[194:197], v[232:235], v[16:19]
	v_mfma_f32_16x16x32_bf16 v[12:15], v[206:209], v[224:227], v[12:15]
	v_mfma_f32_16x16x32_bf16 v[8:11], v[206:209], v[232:235], v[8:11]
	v_mfma_f32_16x16x32_bf16 v[4:7], v[216:219], v[224:227], v[4:7]
	v_mfma_f32_16x16x32_bf16 v[0:3], v[216:219], v[232:235], v[0:3]
	v_mfma_f32_16x16x32_bf16 v[28:31], v[190:193], v[228:231], v[28:31]
	v_mfma_f32_16x16x32_bf16 v[24:27], v[190:193], v[236:239], v[24:27]
	v_mfma_f32_16x16x32_bf16 v[20:23], v[198:201], v[228:231], v[20:23]
	v_mfma_f32_16x16x32_bf16 v[16:19], v[198:201], v[236:239], v[16:19]
	v_mfma_f32_16x16x32_bf16 v[12:15], v[212:215], v[228:231], v[12:15]
	v_mfma_f32_16x16x32_bf16 v[8:11], v[212:215], v[236:239], v[8:11]
	v_mfma_f32_16x16x32_bf16 v[4:7], v[220:223], v[228:231], v[4:7]
	v_mfma_f32_16x16x32_bf16 v[0:3], v[220:223], v[236:239], v[0:3]
	s_setprio 0
	s_add_u32 s6, s6, 0x100
	s_addc_u32 s7, s7, 0
	s_cmp_lt_u32 s11, s10
	s_barrier
	s_cbranch_scc1 .LBB0_219
	v_add_u32_e32 v161, 0xc000, v148
	v_add_u32_e32 v162, 0xe000, v148
	s_or_b32 s6, s60, 0x80
	s_mul_hi_u32 s7, s6, s15
	s_mul_i32 s10, s61, s15
	s_add_i32 s7, s7, s10
	s_mul_i32 s6, s6, s15
	s_lshl_b64 s[6:7], s[6:7], 1
	s_add_u32 s6, s4, s6
	s_addc_u32 s7, s5, s7
	s_add_i32 s36, s12, -1
	s_lshl_b64 s[4:5], s[36:37], 7
	s_add_u32 s4, s6, s4
	s_addc_u32 s5, s7, s5
	v_readfirstlane_b32 s6, v161
	v_lshl_add_u64 v[156:157], v[180:181], 1, s[4:5]
	s_mov_b32 m0, s6
	v_lshl_add_u64 v[128:129], v[128:129], 1, s[4:5]
	v_readfirstlane_b32 s4, v162
	ds_read_b128 v[130:133], v160
	ds_read_b128 v[134:137], v160 offset:1024
	ds_read_b128 v[138:141], v160 offset:2048
	ds_read_b128 v[142:145], v160 offset:3072
	ds_read_b128 v[164:167], v152
	ds_read_b128 v[168:171], v152 offset:1024
	ds_read_b128 v[172:175], v151
	ds_read_b128 v[176:179], v151 offset:1024
	ds_read_b128 v[184:187], v150
	ds_read_b128 v[190:193], v150 offset:1024
	ds_read_b128 v[194:197], v149
	ds_read_b128 v[198:201], v149 offset:1024
	global_load_lds_dwordx4 v[156:157], off
	s_mov_b32 m0, s4
	s_nop 0
	global_load_lds_dwordx4 v[128:129], off
	s_barrier
	s_waitcnt lgkmcnt(0)
	s_setprio 1
	s_waitcnt lgkmcnt(0)
	v_mfma_f32_16x16x32_bf16 v[124:127], v[164:167], v[130:133], v[124:127]
	v_mfma_f32_16x16x32_bf16 v[116:119], v[172:175], v[130:133], v[116:119]
	v_mfma_f32_16x16x32_bf16 v[108:111], v[184:187], v[130:133], v[108:111]
	v_mfma_f32_16x16x32_bf16 v[100:103], v[194:197], v[130:133], v[100:103]
	v_mfma_f32_16x16x32_bf16 v[124:127], v[168:171], v[134:137], v[124:127]
	v_mfma_f32_16x16x32_bf16 v[120:123], v[164:167], v[138:141], v[120:123]
	v_mfma_f32_16x16x32_bf16 v[116:119], v[176:179], v[134:137], v[116:119]
	v_mfma_f32_16x16x32_bf16 v[112:115], v[172:175], v[138:141], v[112:115]
	v_mfma_f32_16x16x32_bf16 v[108:111], v[190:193], v[134:137], v[108:111]
	v_mfma_f32_16x16x32_bf16 v[104:107], v[184:187], v[138:141], v[104:107]
	v_mfma_f32_16x16x32_bf16 v[100:103], v[198:201], v[134:137], v[100:103]
	v_mfma_f32_16x16x32_bf16 v[96:99], v[194:197], v[138:141], v[96:99]
	v_mfma_f32_16x16x32_bf16 v[160:163], v[168:171], v[142:145], v[120:123]
	v_mfma_f32_16x16x32_bf16 v[206:209], v[176:179], v[142:145], v[112:115]
	v_mfma_f32_16x16x32_bf16 v[212:215], v[190:193], v[142:145], v[104:107]
	v_mfma_f32_16x16x32_bf16 v[216:219], v[198:201], v[142:145], v[96:99]
	s_setprio 0
	s_barrier
	s_nop 1
	ds_read_b128 v[96:99], v159
	ds_read_b128 v[104:107], v159 offset:1024
	ds_read_b128 v[112:115], v159 offset:2048
	ds_read_b128 v[120:123], v159 offset:3072
	s_barrier
	s_waitcnt lgkmcnt(0)
	s_setprio 1
	s_waitcnt lgkmcnt(0)
	v_mfma_f32_16x16x32_bf16 v[92:95], v[164:167], v[96:99], v[92:95]
	v_mfma_f32_16x16x32_bf16 v[84:87], v[172:175], v[96:99], v[84:87]
	v_mfma_f32_16x16x32_bf16 v[76:79], v[184:187], v[96:99], v[76:79]
	v_mfma_f32_16x16x32_bf16 v[68:71], v[194:197], v[96:99], v[68:71]
	v_mfma_f32_16x16x32_bf16 v[92:95], v[168:171], v[104:107], v[92:95]
	v_mfma_f32_16x16x32_bf16 v[88:91], v[164:167], v[112:115], v[88:91]
	v_mfma_f32_16x16x32_bf16 v[84:87], v[176:179], v[104:107], v[84:87]
	v_mfma_f32_16x16x32_bf16 v[80:83], v[172:175], v[112:115], v[80:83]
	v_mfma_f32_16x16x32_bf16 v[76:79], v[190:193], v[104:107], v[76:79]
	v_mfma_f32_16x16x32_bf16 v[72:75], v[184:187], v[112:115], v[72:75]
	v_mfma_f32_16x16x32_bf16 v[68:71], v[198:201], v[104:107], v[68:71]
	v_mfma_f32_16x16x32_bf16 v[64:67], v[194:197], v[112:115], v[64:67]
	v_mfma_f32_16x16x32_bf16 v[156:159], v[168:171], v[120:123], v[88:91]
	v_mfma_f32_16x16x32_bf16 v[164:167], v[176:179], v[120:123], v[80:83]
	v_mfma_f32_16x16x32_bf16 v[168:171], v[190:193], v[120:123], v[72:75]
	v_mfma_f32_16x16x32_bf16 v[172:175], v[198:201], v[120:123], v[64:67]
	s_setprio 0
	s_barrier
	s_nop 1
	ds_read_b128 v[64:67], v152 offset:16384
	ds_read_b128 v[72:75], v152 offset:17408
	ds_read_b128 v[80:83], v151 offset:16384
	ds_read_b128 v[88:91], v151 offset:17408
	ds_read_b128 v[176:179], v150 offset:16384
	ds_read_b128 v[184:187], v150 offset:17408
	ds_read_b128 v[190:193], v149 offset:16384
	ds_read_b128 v[194:197], v149 offset:17408
	s_waitcnt vmcnt(4)
	s_barrier
	s_waitcnt lgkmcnt(0)
	s_setprio 1
	s_waitcnt lgkmcnt(0)
	v_mfma_f32_16x16x32_bf16 v[60:63], v[64:67], v[130:133], v[60:63]
	v_mfma_f32_16x16x32_bf16 v[52:55], v[80:83], v[130:133], v[52:55]
	v_mfma_f32_16x16x32_bf16 v[44:47], v[176:179], v[130:133], v[44:47]
	v_mfma_f32_16x16x32_bf16 v[36:39], v[190:193], v[130:133], v[36:39]
	v_mfma_f32_16x16x32_bf16 v[60:63], v[72:75], v[134:137], v[60:63]
	v_mfma_f32_16x16x32_bf16 v[56:59], v[64:67], v[138:141], v[56:59]
	v_mfma_f32_16x16x32_bf16 v[52:55], v[88:91], v[134:137], v[52:55]
	v_mfma_f32_16x16x32_bf16 v[48:51], v[80:83], v[138:141], v[48:51]
	v_mfma_f32_16x16x32_bf16 v[44:47], v[184:187], v[134:137], v[44:47]
	v_mfma_f32_16x16x32_bf16 v[40:43], v[176:179], v[138:141], v[40:43]
	v_mfma_f32_16x16x32_bf16 v[36:39], v[194:197], v[134:137], v[36:39]
	v_mfma_f32_16x16x32_bf16 v[32:35], v[190:193], v[138:141], v[32:35]
	v_mfma_f32_16x16x32_bf16 v[198:201], v[72:75], v[142:145], v[56:59]
	v_mfma_f32_16x16x32_bf16 v[220:223], v[88:91], v[142:145], v[48:51]
	v_mfma_f32_16x16x32_bf16 v[224:227], v[184:187], v[142:145], v[40:43]
	v_mfma_f32_16x16x32_bf16 v[128:131], v[194:197], v[142:145], v[32:35]
	s_setprio 0
	s_setprio 1
	v_mfma_f32_16x16x32_bf16 v[28:31], v[64:67], v[96:99], v[28:31]
	v_mfma_f32_16x16x32_bf16 v[20:23], v[80:83], v[96:99], v[20:23]
	v_mfma_f32_16x16x32_bf16 v[12:15], v[176:179], v[96:99], v[12:15]
	v_mfma_f32_16x16x32_bf16 v[4:7], v[190:193], v[96:99], v[4:7]
	v_mfma_f32_16x16x32_bf16 v[28:31], v[72:75], v[104:107], v[28:31]
	v_mfma_f32_16x16x32_bf16 v[24:27], v[64:67], v[112:115], v[24:27]
	v_mfma_f32_16x16x32_bf16 v[20:23], v[88:91], v[104:107], v[20:23]
	v_mfma_f32_16x16x32_bf16 v[16:19], v[80:83], v[112:115], v[16:19]
	v_mfma_f32_16x16x32_bf16 v[12:15], v[184:187], v[104:107], v[12:15]
	v_mfma_f32_16x16x32_bf16 v[8:11], v[176:179], v[112:115], v[8:11]
	v_mfma_f32_16x16x32_bf16 v[4:7], v[194:197], v[104:107], v[4:7]
	v_mfma_f32_16x16x32_bf16 v[0:3], v[190:193], v[112:115], v[0:3]
	v_mfma_f32_16x16x32_bf16 v[132:135], v[72:75], v[120:123], v[24:27]
	v_mfma_f32_16x16x32_bf16 v[136:139], v[88:91], v[120:123], v[16:19]
	v_mfma_f32_16x16x32_bf16 v[140:143], v[184:187], v[120:123], v[8:11]
	v_mfma_f32_16x16x32_bf16 v[176:179], v[194:197], v[120:123], v[0:3]
	s_setprio 0
	s_barrier
	s_nop 1
	ds_read_b128 v[0:3], v155
	ds_read_b128 v[8:11], v155 offset:1024
	ds_read_b128 v[16:19], v155 offset:2048
	ds_read_b128 v[24:27], v155 offset:3072
	ds_read_b128 v[32:35], v152 offset:32768
	ds_read_b128 v[40:43], v152 offset:33792
	ds_read_b128 v[48:51], v151 offset:32768
	ds_read_b128 v[56:59], v151 offset:33792
	ds_read_b128 v[64:67], v150 offset:32768
	ds_read_b128 v[184:187], v150 offset:33792
	ds_read_b128 v[190:193], v149 offset:32768
	ds_read_b128 v[194:197], v149 offset:33792
	s_waitcnt vmcnt(2)
	s_barrier
	s_waitcnt lgkmcnt(0)
	s_setprio 1
	s_waitcnt lgkmcnt(0)
	v_mfma_f32_16x16x32_bf16 v[72:75], v[32:35], v[0:3], v[124:127]
	v_mfma_f32_16x16x32_bf16 v[120:123], v[40:43], v[8:11], v[72:75]
	v_mfma_f32_16x16x32_bf16 v[72:75], v[32:35], v[16:19], v[160:163]
	v_mfma_f32_16x16x32_bf16 v[124:127], v[40:43], v[24:27], v[72:75]
	v_mfma_f32_16x16x32_bf16 v[72:75], v[48:51], v[0:3], v[116:119]
	v_mfma_f32_16x16x32_bf16 v[112:115], v[56:59], v[8:11], v[72:75]
	v_mfma_f32_16x16x32_bf16 v[72:75], v[48:51], v[16:19], v[206:209]
	v_mfma_f32_16x16x32_bf16 v[116:119], v[56:59], v[24:27], v[72:75]
	v_mfma_f32_16x16x32_bf16 v[72:75], v[64:67], v[0:3], v[108:111]
	v_mfma_f32_16x16x32_bf16 v[104:107], v[184:187], v[8:11], v[72:75]
	v_mfma_f32_16x16x32_bf16 v[72:75], v[64:67], v[16:19], v[212:215]
	v_mfma_f32_16x16x32_bf16 v[108:111], v[184:187], v[24:27], v[72:75]
	v_mfma_f32_16x16x32_bf16 v[72:75], v[190:193], v[0:3], v[100:103]
	v_mfma_f32_16x16x32_bf16 v[96:99], v[194:197], v[8:11], v[72:75]
	v_mfma_f32_16x16x32_bf16 v[72:75], v[190:193], v[16:19], v[216:219]
	v_mfma_f32_16x16x32_bf16 v[100:103], v[194:197], v[24:27], v[72:75]
	s_setprio 0
	s_barrier
	ds_read_b128 v[160:163], v153
	ds_read_b128 v[206:209], v153 offset:1024
	ds_read_b128 v[212:215], v153 offset:2048
	ds_read_b128 v[216:219], v153 offset:3072
	s_waitcnt vmcnt(0)
	s_barrier
	s_waitcnt lgkmcnt(0)
	s_setprio 1
	s_waitcnt lgkmcnt(0)
	v_mfma_f32_16x16x32_bf16 v[72:75], v[32:35], v[160:163], v[92:95]
	v_mfma_f32_16x16x32_bf16 v[32:35], v[32:35], v[212:215], v[156:159]
	v_mfma_f32_16x16x32_bf16 v[92:95], v[40:43], v[216:219], v[32:35]
	v_mfma_f32_16x16x32_bf16 v[32:35], v[48:51], v[160:163], v[84:87]
	v_mfma_f32_16x16x32_bf16 v[80:83], v[56:59], v[206:209], v[32:35]
	v_mfma_f32_16x16x32_bf16 v[32:35], v[48:51], v[212:215], v[164:167]
	v_mfma_f32_16x16x32_bf16 v[84:87], v[56:59], v[216:219], v[32:35]
	v_mfma_f32_16x16x32_bf16 v[32:35], v[64:67], v[160:163], v[76:79]
	v_mfma_f32_16x16x32_bf16 v[88:91], v[40:43], v[206:209], v[72:75]
	v_mfma_f32_16x16x32_bf16 v[72:75], v[184:187], v[206:209], v[32:35]
	v_mfma_f32_16x16x32_bf16 v[32:35], v[64:67], v[212:215], v[168:171]
	v_mfma_f32_16x16x32_bf16 v[76:79], v[184:187], v[216:219], v[32:35]
	v_mfma_f32_16x16x32_bf16 v[32:35], v[190:193], v[160:163], v[68:71]
	v_mfma_f32_16x16x32_bf16 v[64:67], v[194:197], v[206:209], v[32:35]
	v_mfma_f32_16x16x32_bf16 v[32:35], v[190:193], v[212:215], v[172:175]
	v_mfma_f32_16x16x32_bf16 v[68:71], v[194:197], v[216:219], v[32:35]
	s_setprio 0
	s_barrier
	ds_read_b128 v[154:157], v152 offset:49152
	ds_read_b128 v[164:167], v152 offset:50176
	ds_read_b128 v[168:171], v151 offset:49152
	ds_read_b128 v[172:175], v151 offset:50176
	ds_read_b128 v[184:187], v150 offset:49152
	ds_read_b128 v[150:153], v150 offset:50176
	ds_read_b128 v[190:193], v149 offset:49152
	ds_read_b128 v[194:197], v149 offset:50176
	s_barrier
	s_waitcnt lgkmcnt(0)
	s_setprio 1
	s_waitcnt lgkmcnt(0)
	v_mfma_f32_16x16x32_bf16 v[32:35], v[154:157], v[0:3], v[60:63]
	v_mfma_f32_16x16x32_bf16 v[56:59], v[164:167], v[8:11], v[32:35]
	v_mfma_f32_16x16x32_bf16 v[32:35], v[154:157], v[16:19], v[198:201]
	v_mfma_f32_16x16x32_bf16 v[60:63], v[164:167], v[24:27], v[32:35]
	v_mfma_f32_16x16x32_bf16 v[32:35], v[168:171], v[0:3], v[52:55]
	v_mfma_f32_16x16x32_bf16 v[48:51], v[172:175], v[8:11], v[32:35]
	v_mfma_f32_16x16x32_bf16 v[32:35], v[168:171], v[16:19], v[220:223]
	v_mfma_f32_16x16x32_bf16 v[52:55], v[172:175], v[24:27], v[32:35]
	v_mfma_f32_16x16x32_bf16 v[32:35], v[184:187], v[0:3], v[44:47]
	v_mfma_f32_16x16x32_bf16 v[40:43], v[150:153], v[8:11], v[32:35]
	v_mfma_f32_16x16x32_bf16 v[32:35], v[184:187], v[16:19], v[224:227]
	v_mfma_f32_16x16x32_bf16 v[0:3], v[190:193], v[0:3], v[36:39]
	v_mfma_f32_16x16x32_bf16 v[44:47], v[150:153], v[24:27], v[32:35]
	v_mfma_f32_16x16x32_bf16 v[32:35], v[194:197], v[8:11], v[0:3]
	v_mfma_f32_16x16x32_bf16 v[0:3], v[190:193], v[16:19], v[128:131]
	v_mfma_f32_16x16x32_bf16 v[36:39], v[194:197], v[24:27], v[0:3]
	s_setprio 0
	s_setprio 1
	v_mfma_f32_16x16x32_bf16 v[0:3], v[154:157], v[160:163], v[28:31]
	v_mfma_f32_16x16x32_bf16 v[24:27], v[164:167], v[206:209], v[0:3]
	v_mfma_f32_16x16x32_bf16 v[0:3], v[154:157], v[212:215], v[132:135]
	v_mfma_f32_16x16x32_bf16 v[28:31], v[164:167], v[216:219], v[0:3]
	v_mfma_f32_16x16x32_bf16 v[0:3], v[168:171], v[160:163], v[20:23]
	v_mfma_f32_16x16x32_bf16 v[16:19], v[172:175], v[206:209], v[0:3]
	v_mfma_f32_16x16x32_bf16 v[0:3], v[168:171], v[212:215], v[136:139]
	v_mfma_f32_16x16x32_bf16 v[20:23], v[172:175], v[216:219], v[0:3]
	v_mfma_f32_16x16x32_bf16 v[0:3], v[184:187], v[160:163], v[12:15]
	v_mfma_f32_16x16x32_bf16 v[8:11], v[150:153], v[206:209], v[0:3]
	v_mfma_f32_16x16x32_bf16 v[0:3], v[184:187], v[212:215], v[140:143]
	v_mfma_f32_16x16x32_bf16 v[12:15], v[150:153], v[216:219], v[0:3]
	v_mfma_f32_16x16x32_bf16 v[0:3], v[190:193], v[160:163], v[4:7]
	v_mfma_f32_16x16x32_bf16 v[4:7], v[190:193], v[212:215], v[176:179]
	v_mfma_f32_16x16x32_bf16 v[0:3], v[194:197], v[206:209], v[0:3]
	v_mfma_f32_16x16x32_bf16 v[4:7], v[194:197], v[216:219], v[4:7]
	s_setprio 0
	s_movk_i32 s4, 0x100
	v_cmp_gt_u32_e32 vcc, s4, v146
	s_barrier
	s_and_saveexec_b64 s[4:5], vcc
	s_cbranch_execz .LBB0_222
	s_barrier
